# ffn_in epilogue: alignment barrier of the leading half moved behind its first row block of the second epilogue half
# speedup vs baseline: 1.0001x; 1.0001x over previous
.LBB0_78:
	s_and_b64 vcc, exec, s[20:21]
	s_cbranch_vccz .LBB0_80
	s_nop 0
.LBB0_80:
	v_add_u32_e32 v235, 0x84000, v235
	v_add_u32_e32 v234, 0x21800, v151
	ds_read_b128 v[236:239], v234
	ds_read_b128 v[240:243], v234 offset:256
	ds_read_b128 v[244:247], v234 offset:512
	ds_read_b128 v[248:251], v234 offset:768
	s_waitcnt lgkmcnt(0)
	v_add_f32_e32 v236, v236, v237
	v_add_f32_e32 v238, v238, v239
	v_add_f32_e32 v240, v240, v241
	v_add_f32_e32 v242, v242, v243
	v_add_f32_e32 v244, v244, v245
	v_add_f32_e32 v246, v246, v247
	v_add_f32_e32 v248, v248, v249
	v_add_f32_e32 v250, v250, v251
	v_add_f32_e32 v236, v236, v238
	v_add_f32_e32 v240, v240, v242
	v_add_f32_e32 v244, v244, v246
	v_add_f32_e32 v248, v248, v250
	v_fmamk_f32 v236, v236, 0x3a800000, v152
	v_fmamk_f32 v240, v240, 0x3a800000, v152
	v_fmamk_f32 v244, v244, 0x3a800000, v152
	v_fmamk_f32 v248, v248, 0x3a800000, v152
	v_rsq_f32_e32 v236, v236
	v_rsq_f32_e32 v240, v240
	v_rsq_f32_e32 v244, v244
	v_rsq_f32_e32 v248, v248
	v_mul_f32_e32 v252, 0xbfb8aa3b, v236
	v_mul_f32_e32 v254, v236, v236
	v_rcp_f32_e32 v254, v254
	v_pk_mul_f32 v[56:57], v[60:61], v[56:57]
	v_pk_mul_f32 v[58:59], v[62:63], v[58:59]
	v_pk_mul_f32 v[48:49], v[52:53], v[48:49]
	v_pk_mul_f32 v[50:51], v[54:55], v[50:51]
	v_pk_mul_f32 v[60:61], v[60:61], v[252:253] op_sel_hi:[1,0]
	v_pk_mul_f32 v[62:63], v[62:63], v[252:253] op_sel_hi:[1,0]
	v_pk_mul_f32 v[52:53], v[52:53], v[252:253] op_sel_hi:[1,0]
	v_pk_mul_f32 v[54:55], v[54:55], v[252:253] op_sel_hi:[1,0]
	v_exp_f32_e32 v60, v60
	v_exp_f32_e32 v61, v61
	v_exp_f32_e32 v62, v62
	v_exp_f32_e32 v63, v63
	v_exp_f32_e32 v52, v52
	v_exp_f32_e32 v53, v53
	v_exp_f32_e32 v54, v54
	v_exp_f32_e32 v55, v55
	v_pk_fma_f32 v[60:61], v[60:61], v[254:255], v[254:255] op_sel_hi:[1,0,0]
	v_pk_fma_f32 v[62:63], v[62:63], v[254:255], v[254:255] op_sel_hi:[1,0,0]
	v_pk_fma_f32 v[52:53], v[52:53], v[254:255], v[254:255] op_sel_hi:[1,0,0]
	v_pk_fma_f32 v[54:55], v[54:55], v[254:255], v[254:255] op_sel_hi:[1,0,0]
	v_rcp_f32_e32 v60, v60
	v_rcp_f32_e32 v61, v61
	v_rcp_f32_e32 v62, v62
	v_rcp_f32_e32 v63, v63
	v_rcp_f32_e32 v52, v52
	v_rcp_f32_e32 v53, v53
	v_rcp_f32_e32 v54, v54
	v_rcp_f32_e32 v55, v55
	v_pk_mul_f32 v[56:57], v[56:57], v[60:61]
	v_pk_mul_f32 v[58:59], v[58:59], v[62:63]
	v_pk_mul_f32 v[48:49], v[48:49], v[52:53]
	v_pk_mul_f32 v[50:51], v[50:51], v[54:55]
	v_cvt_pk_bf16_f32 v56, v56, v57
	v_cvt_pk_bf16_f32 v57, v58, v59
	v_cvt_pk_bf16_f32 v58, v48, v49
	v_cvt_pk_bf16_f32 v59, v50, v51
	global_store_dwordx4 v235, v[56:59], s[10:11]
	s_and_b64 vcc, exec, s[20:21]
	s_cbranch_vccz .Lal_0
	s_barrier
.Lal_0:
	v_add_u32_e32 v234, 0x16000, v235
	v_mul_f32_e32 v252, 0xbfb8aa3b, v240
	v_mul_f32_e32 v254, v240, v240
	v_rcp_f32_e32 v254, v254
	v_pk_mul_f32 v[40:41], v[44:45], v[40:41]
	v_pk_mul_f32 v[42:43], v[46:47], v[42:43]
	v_pk_mul_f32 v[32:33], v[36:37], v[32:33]
	v_pk_mul_f32 v[34:35], v[38:39], v[34:35]
	v_pk_mul_f32 v[44:45], v[44:45], v[252:253] op_sel_hi:[1,0]
	v_pk_mul_f32 v[46:47], v[46:47], v[252:253] op_sel_hi:[1,0]
	v_pk_mul_f32 v[36:37], v[36:37], v[252:253] op_sel_hi:[1,0]
	v_pk_mul_f32 v[38:39], v[38:39], v[252:253] op_sel_hi:[1,0]
	v_exp_f32_e32 v44, v44
	v_exp_f32_e32 v45, v45
	v_exp_f32_e32 v46, v46
	v_exp_f32_e32 v47, v47
	v_exp_f32_e32 v36, v36
	v_exp_f32_e32 v37, v37
	v_exp_f32_e32 v38, v38
	v_exp_f32_e32 v39, v39
	v_pk_fma_f32 v[44:45], v[44:45], v[254:255], v[254:255] op_sel_hi:[1,0,0]
	v_pk_fma_f32 v[46:47], v[46:47], v[254:255], v[254:255] op_sel_hi:[1,0,0]
	v_pk_fma_f32 v[36:37], v[36:37], v[254:255], v[254:255] op_sel_hi:[1,0,0]
	v_pk_fma_f32 v[38:39], v[38:39], v[254:255], v[254:255] op_sel_hi:[1,0,0]
	v_rcp_f32_e32 v44, v44
	v_rcp_f32_e32 v45, v45
	v_rcp_f32_e32 v46, v46
	v_rcp_f32_e32 v47, v47
	v_rcp_f32_e32 v36, v36
	v_rcp_f32_e32 v37, v37
	v_rcp_f32_e32 v38, v38
	v_rcp_f32_e32 v39, v39
	v_pk_mul_f32 v[40:41], v[40:41], v[44:45]
	v_pk_mul_f32 v[42:43], v[42:43], v[46:47]
	v_pk_mul_f32 v[32:33], v[32:33], v[36:37]
	v_pk_mul_f32 v[34:35], v[34:35], v[38:39]
	v_cvt_pk_bf16_f32 v40, v40, v41
	v_cvt_pk_bf16_f32 v41, v42, v43
	v_cvt_pk_bf16_f32 v42, v32, v33
	v_cvt_pk_bf16_f32 v43, v34, v35
	global_store_dwordx4 v234, v[40:43], s[10:11]
	v_add_u32_e32 v235, 0x16000, v234
	v_mul_f32_e32 v252, 0xbfb8aa3b, v244
	v_mul_f32_e32 v254, v244, v244
	v_rcp_f32_e32 v254, v254
	v_pk_mul_f32 v[24:25], v[28:29], v[24:25]
	v_pk_mul_f32 v[26:27], v[30:31], v[26:27]
	v_pk_mul_f32 v[16:17], v[20:21], v[16:17]
	v_pk_mul_f32 v[18:19], v[22:23], v[18:19]
	v_pk_mul_f32 v[28:29], v[28:29], v[252:253] op_sel_hi:[1,0]
	v_pk_mul_f32 v[30:31], v[30:31], v[252:253] op_sel_hi:[1,0]
	v_pk_mul_f32 v[20:21], v[20:21], v[252:253] op_sel_hi:[1,0]
	v_pk_mul_f32 v[22:23], v[22:23], v[252:253] op_sel_hi:[1,0]
	v_exp_f32_e32 v28, v28
	v_exp_f32_e32 v29, v29
	v_exp_f32_e32 v30, v30
	v_exp_f32_e32 v31, v31
	v_exp_f32_e32 v20, v20
	v_exp_f32_e32 v21, v21
	v_exp_f32_e32 v22, v22
	v_exp_f32_e32 v23, v23
	v_pk_fma_f32 v[28:29], v[28:29], v[254:255], v[254:255] op_sel_hi:[1,0,0]
	v_pk_fma_f32 v[30:31], v[30:31], v[254:255], v[254:255] op_sel_hi:[1,0,0]
	v_pk_fma_f32 v[20:21], v[20:21], v[254:255], v[254:255] op_sel_hi:[1,0,0]
	v_pk_fma_f32 v[22:23], v[22:23], v[254:255], v[254:255] op_sel_hi:[1,0,0]
	v_rcp_f32_e32 v28, v28
	v_rcp_f32_e32 v29, v29
	v_rcp_f32_e32 v30, v30
	v_rcp_f32_e32 v31, v31
	v_rcp_f32_e32 v20, v20
	v_rcp_f32_e32 v21, v21
	v_rcp_f32_e32 v22, v22
	v_rcp_f32_e32 v23, v23
	v_pk_mul_f32 v[24:25], v[24:25], v[28:29]
	v_pk_mul_f32 v[26:27], v[26:27], v[30:31]
	v_pk_mul_f32 v[16:17], v[16:17], v[20:21]
	v_pk_mul_f32 v[18:19], v[18:19], v[22:23]
	v_cvt_pk_bf16_f32 v24, v24, v25
	v_cvt_pk_bf16_f32 v25, v26, v27
	v_cvt_pk_bf16_f32 v26, v16, v17
	v_cvt_pk_bf16_f32 v27, v18, v19
	global_store_dwordx4 v235, v[24:27], s[10:11]
	v_add_u32_e32 v234, 0x16000, v235
	v_mul_f32_e32 v252, 0xbfb8aa3b, v248
	v_mul_f32_e32 v254, v248, v248
	v_rcp_f32_e32 v254, v254
	v_pk_mul_f32 v[8:9], v[12:13], v[8:9]
	v_pk_mul_f32 v[10:11], v[14:15], v[10:11]
	v_pk_mul_f32 v[0:1], v[4:5], v[0:1]
	v_pk_mul_f32 v[2:3], v[6:7], v[2:3]
	v_pk_mul_f32 v[12:13], v[12:13], v[252:253] op_sel_hi:[1,0]
	v_pk_mul_f32 v[14:15], v[14:15], v[252:253] op_sel_hi:[1,0]
	v_pk_mul_f32 v[4:5], v[4:5], v[252:253] op_sel_hi:[1,0]
	v_pk_mul_f32 v[6:7], v[6:7], v[252:253] op_sel_hi:[1,0]
	v_exp_f32_e32 v12, v12
	v_exp_f32_e32 v13, v13
	v_exp_f32_e32 v14, v14
	v_exp_f32_e32 v15, v15
	v_exp_f32_e32 v4, v4
	v_exp_f32_e32 v5, v5
	v_exp_f32_e32 v6, v6
	v_exp_f32_e32 v7, v7
	v_pk_fma_f32 v[12:13], v[12:13], v[254:255], v[254:255] op_sel_hi:[1,0,0]
	v_pk_fma_f32 v[14:15], v[14:15], v[254:255], v[254:255] op_sel_hi:[1,0,0]
	v_pk_fma_f32 v[4:5], v[4:5], v[254:255], v[254:255] op_sel_hi:[1,0,0]
	v_pk_fma_f32 v[6:7], v[6:7], v[254:255], v[254:255] op_sel_hi:[1,0,0]
	v_rcp_f32_e32 v12, v12
	v_rcp_f32_e32 v13, v13
	v_rcp_f32_e32 v14, v14
	v_rcp_f32_e32 v15, v15
	v_rcp_f32_e32 v4, v4
	v_rcp_f32_e32 v5, v5
	v_rcp_f32_e32 v6, v6
	v_rcp_f32_e32 v7, v7
	v_pk_mul_f32 v[8:9], v[8:9], v[12:13]
	v_pk_mul_f32 v[10:11], v[10:11], v[14:15]
	v_pk_mul_f32 v[0:1], v[0:1], v[4:5]
	v_pk_mul_f32 v[2:3], v[2:3], v[6:7]
	v_cvt_pk_bf16_f32 v8, v8, v9
	v_cvt_pk_bf16_f32 v9, v10, v11
	v_cvt_pk_bf16_f32 v10, v0, v1
	v_cvt_pk_bf16_f32 v11, v2, v3
	global_store_dwordx4 v234, v[8:11], s[10:11]
	s_andn2_b64 vcc, exec, s[4:5]
	s_mov_b64 s[4:5], -1
	s_cbranch_vccnz .LBB0_71
	s_andn2_b64 vcc, exec, s[8:9]
	s_cbranch_vccnz .LBB0_70
	s_barrier
	s_branch .LBB0_70

.LBB0_529:
	s_and_b64 vcc, exec, s[24:25]
	s_cbranch_vccz .LBB0_531
	s_nop 0
.LBB0_531:
	v_add_u32_e32 v235, 0x84000, v235
	v_add_u32_e32 v234, 0x21800, v151
	ds_read_b128 v[236:239], v234
	ds_read_b128 v[240:243], v234 offset:256
	ds_read_b128 v[244:247], v234 offset:512
	ds_read_b128 v[248:251], v234 offset:768
	s_waitcnt lgkmcnt(0)
	v_add_f32_e32 v236, v236, v237
	v_add_f32_e32 v238, v238, v239
	v_add_f32_e32 v240, v240, v241
	v_add_f32_e32 v242, v242, v243
	v_add_f32_e32 v244, v244, v245
	v_add_f32_e32 v246, v246, v247
	v_add_f32_e32 v248, v248, v249
	v_add_f32_e32 v250, v250, v251
	v_add_f32_e32 v236, v236, v238
	v_add_f32_e32 v240, v240, v242
	v_add_f32_e32 v244, v244, v246
	v_add_f32_e32 v248, v248, v250
	v_fmamk_f32 v236, v236, 0x3a800000, v152
	v_fmamk_f32 v240, v240, 0x3a800000, v152
	v_fmamk_f32 v244, v244, 0x3a800000, v152
	v_fmamk_f32 v248, v248, 0x3a800000, v152
	v_rsq_f32_e32 v236, v236
	v_rsq_f32_e32 v240, v240
	v_rsq_f32_e32 v244, v244
	v_rsq_f32_e32 v248, v248
	v_mul_f32_e32 v252, 0xbfb8aa3b, v236
	v_mul_f32_e32 v254, v236, v236
	v_rcp_f32_e32 v254, v254
	v_pk_mul_f32 v[56:57], v[60:61], v[56:57]
	v_pk_mul_f32 v[58:59], v[62:63], v[58:59]
	v_pk_mul_f32 v[48:49], v[52:53], v[48:49]
	v_pk_mul_f32 v[50:51], v[54:55], v[50:51]
	v_pk_mul_f32 v[60:61], v[60:61], v[252:253] op_sel_hi:[1,0]
	v_pk_mul_f32 v[62:63], v[62:63], v[252:253] op_sel_hi:[1,0]
	v_pk_mul_f32 v[52:53], v[52:53], v[252:253] op_sel_hi:[1,0]
	v_pk_mul_f32 v[54:55], v[54:55], v[252:253] op_sel_hi:[1,0]
	v_exp_f32_e32 v60, v60
	v_exp_f32_e32 v61, v61
	v_exp_f32_e32 v62, v62
	v_exp_f32_e32 v63, v63
	v_exp_f32_e32 v52, v52
	v_exp_f32_e32 v53, v53
	v_exp_f32_e32 v54, v54
	v_exp_f32_e32 v55, v55
	v_pk_fma_f32 v[60:61], v[60:61], v[254:255], v[254:255] op_sel_hi:[1,0,0]
	v_pk_fma_f32 v[62:63], v[62:63], v[254:255], v[254:255] op_sel_hi:[1,0,0]
	v_pk_fma_f32 v[52:53], v[52:53], v[254:255], v[254:255] op_sel_hi:[1,0,0]
	v_pk_fma_f32 v[54:55], v[54:55], v[254:255], v[254:255] op_sel_hi:[1,0,0]
	v_rcp_f32_e32 v60, v60
	v_rcp_f32_e32 v61, v61
	v_rcp_f32_e32 v62, v62
	v_rcp_f32_e32 v63, v63
	v_rcp_f32_e32 v52, v52
	v_rcp_f32_e32 v53, v53
	v_rcp_f32_e32 v54, v54
	v_rcp_f32_e32 v55, v55
	v_pk_mul_f32 v[56:57], v[56:57], v[60:61]
	v_pk_mul_f32 v[58:59], v[58:59], v[62:63]
	v_pk_mul_f32 v[48:49], v[48:49], v[52:53]
	v_pk_mul_f32 v[50:51], v[50:51], v[54:55]
	v_cvt_pk_bf16_f32 v56, v56, v57
	v_cvt_pk_bf16_f32 v57, v58, v59
	v_cvt_pk_bf16_f32 v58, v48, v49
	v_cvt_pk_bf16_f32 v59, v50, v51
	global_store_dwordx4 v235, v[56:59], s[14:15]
	s_and_b64 vcc, exec, s[24:25]
	s_cbranch_vccz .Lal_4
	s_barrier
.Lal_4:
	v_add_u32_e32 v234, 0x16000, v235
	v_mul_f32_e32 v252, 0xbfb8aa3b, v240
	v_mul_f32_e32 v254, v240, v240
	v_rcp_f32_e32 v254, v254
	v_pk_mul_f32 v[40:41], v[44:45], v[40:41]
	v_pk_mul_f32 v[42:43], v[46:47], v[42:43]
	v_pk_mul_f32 v[32:33], v[36:37], v[32:33]
	v_pk_mul_f32 v[34:35], v[38:39], v[34:35]
	v_pk_mul_f32 v[44:45], v[44:45], v[252:253] op_sel_hi:[1,0]
	v_pk_mul_f32 v[46:47], v[46:47], v[252:253] op_sel_hi:[1,0]
	v_pk_mul_f32 v[36:37], v[36:37], v[252:253] op_sel_hi:[1,0]
	v_pk_mul_f32 v[38:39], v[38:39], v[252:253] op_sel_hi:[1,0]
	v_exp_f32_e32 v44, v44
	v_exp_f32_e32 v45, v45
	v_exp_f32_e32 v46, v46
	v_exp_f32_e32 v47, v47
	v_exp_f32_e32 v36, v36
	v_exp_f32_e32 v37, v37
	v_exp_f32_e32 v38, v38
	v_exp_f32_e32 v39, v39
	v_pk_fma_f32 v[44:45], v[44:45], v[254:255], v[254:255] op_sel_hi:[1,0,0]
	v_pk_fma_f32 v[46:47], v[46:47], v[254:255], v[254:255] op_sel_hi:[1,0,0]
	v_pk_fma_f32 v[36:37], v[36:37], v[254:255], v[254:255] op_sel_hi:[1,0,0]
	v_pk_fma_f32 v[38:39], v[38:39], v[254:255], v[254:255] op_sel_hi:[1,0,0]
	v_rcp_f32_e32 v44, v44
	v_rcp_f32_e32 v45, v45
	v_rcp_f32_e32 v46, v46
	v_rcp_f32_e32 v47, v47
	v_rcp_f32_e32 v36, v36
	v_rcp_f32_e32 v37, v37
	v_rcp_f32_e32 v38, v38
	v_rcp_f32_e32 v39, v39
	v_pk_mul_f32 v[40:41], v[40:41], v[44:45]
	v_pk_mul_f32 v[42:43], v[42:43], v[46:47]
	v_pk_mul_f32 v[32:33], v[32:33], v[36:37]
	v_pk_mul_f32 v[34:35], v[34:35], v[38:39]
	v_cvt_pk_bf16_f32 v40, v40, v41
	v_cvt_pk_bf16_f32 v41, v42, v43
	v_cvt_pk_bf16_f32 v42, v32, v33
	v_cvt_pk_bf16_f32 v43, v34, v35
	global_store_dwordx4 v234, v[40:43], s[14:15]
	v_add_u32_e32 v235, 0x16000, v234
	v_mul_f32_e32 v252, 0xbfb8aa3b, v244
	v_mul_f32_e32 v254, v244, v244
	v_rcp_f32_e32 v254, v254
	v_pk_mul_f32 v[24:25], v[28:29], v[24:25]
	v_pk_mul_f32 v[26:27], v[30:31], v[26:27]
	v_pk_mul_f32 v[16:17], v[20:21], v[16:17]
	v_pk_mul_f32 v[18:19], v[22:23], v[18:19]
	v_pk_mul_f32 v[28:29], v[28:29], v[252:253] op_sel_hi:[1,0]
	v_pk_mul_f32 v[30:31], v[30:31], v[252:253] op_sel_hi:[1,0]
	v_pk_mul_f32 v[20:21], v[20:21], v[252:253] op_sel_hi:[1,0]
	v_pk_mul_f32 v[22:23], v[22:23], v[252:253] op_sel_hi:[1,0]
	v_exp_f32_e32 v28, v28
	v_exp_f32_e32 v29, v29
	v_exp_f32_e32 v30, v30
	v_exp_f32_e32 v31, v31
	v_exp_f32_e32 v20, v20
	v_exp_f32_e32 v21, v21
	v_exp_f32_e32 v22, v22
	v_exp_f32_e32 v23, v23
	v_pk_fma_f32 v[28:29], v[28:29], v[254:255], v[254:255] op_sel_hi:[1,0,0]
	v_pk_fma_f32 v[30:31], v[30:31], v[254:255], v[254:255] op_sel_hi:[1,0,0]
	v_pk_fma_f32 v[20:21], v[20:21], v[254:255], v[254:255] op_sel_hi:[1,0,0]
	v_pk_fma_f32 v[22:23], v[22:23], v[254:255], v[254:255] op_sel_hi:[1,0,0]
	v_rcp_f32_e32 v28, v28
	v_rcp_f32_e32 v29, v29
	v_rcp_f32_e32 v30, v30
	v_rcp_f32_e32 v31, v31
	v_rcp_f32_e32 v20, v20
	v_rcp_f32_e32 v21, v21
	v_rcp_f32_e32 v22, v22
	v_rcp_f32_e32 v23, v23
	v_pk_mul_f32 v[24:25], v[24:25], v[28:29]
	v_pk_mul_f32 v[26:27], v[26:27], v[30:31]
	v_pk_mul_f32 v[16:17], v[16:17], v[20:21]
	v_pk_mul_f32 v[18:19], v[18:19], v[22:23]
	v_cvt_pk_bf16_f32 v24, v24, v25
	v_cvt_pk_bf16_f32 v25, v26, v27
	v_cvt_pk_bf16_f32 v26, v16, v17
	v_cvt_pk_bf16_f32 v27, v18, v19
	global_store_dwordx4 v235, v[24:27], s[14:15]
	v_add_u32_e32 v234, 0x16000, v235
	v_mul_f32_e32 v252, 0xbfb8aa3b, v248
	v_mul_f32_e32 v254, v248, v248
	v_rcp_f32_e32 v254, v254
	v_pk_mul_f32 v[8:9], v[12:13], v[8:9]
	v_pk_mul_f32 v[10:11], v[14:15], v[10:11]
	v_pk_mul_f32 v[0:1], v[4:5], v[0:1]
	v_pk_mul_f32 v[2:3], v[6:7], v[2:3]
	v_pk_mul_f32 v[12:13], v[12:13], v[252:253] op_sel_hi:[1,0]
	v_pk_mul_f32 v[14:15], v[14:15], v[252:253] op_sel_hi:[1,0]
	v_pk_mul_f32 v[4:5], v[4:5], v[252:253] op_sel_hi:[1,0]
	v_pk_mul_f32 v[6:7], v[6:7], v[252:253] op_sel_hi:[1,0]
	v_exp_f32_e32 v12, v12
	v_exp_f32_e32 v13, v13
	v_exp_f32_e32 v14, v14
	v_exp_f32_e32 v15, v15
	v_exp_f32_e32 v4, v4
	v_exp_f32_e32 v5, v5
	v_exp_f32_e32 v6, v6
	v_exp_f32_e32 v7, v7
	v_pk_fma_f32 v[12:13], v[12:13], v[254:255], v[254:255] op_sel_hi:[1,0,0]
	v_pk_fma_f32 v[14:15], v[14:15], v[254:255], v[254:255] op_sel_hi:[1,0,0]
	v_pk_fma_f32 v[4:5], v[4:5], v[254:255], v[254:255] op_sel_hi:[1,0,0]
	v_pk_fma_f32 v[6:7], v[6:7], v[254:255], v[254:255] op_sel_hi:[1,0,0]
	v_rcp_f32_e32 v12, v12
	v_rcp_f32_e32 v13, v13
	v_rcp_f32_e32 v14, v14
	v_rcp_f32_e32 v15, v15
	v_rcp_f32_e32 v4, v4
	v_rcp_f32_e32 v5, v5
	v_rcp_f32_e32 v6, v6
	v_rcp_f32_e32 v7, v7
	v_pk_mul_f32 v[8:9], v[8:9], v[12:13]
	v_pk_mul_f32 v[10:11], v[10:11], v[14:15]
	v_pk_mul_f32 v[0:1], v[0:1], v[4:5]
	v_pk_mul_f32 v[2:3], v[2:3], v[6:7]
	v_cvt_pk_bf16_f32 v8, v8, v9
	v_cvt_pk_bf16_f32 v9, v10, v11
	v_cvt_pk_bf16_f32 v10, v0, v1
	v_cvt_pk_bf16_f32 v11, v2, v3
	global_store_dwordx4 v234, v[8:11], s[14:15]
	s_andn2_b64 vcc, exec, s[10:11]
	s_mov_b64 s[10:11], -1
	s_cbranch_vccnz .LBB0_522
	s_andn2_b64 vcc, exec, s[12:13]
	s_cbranch_vccnz .LBB0_521
	s_barrier
	s_branch .LBB0_521

.Lal_10:
	v_add_u32_e32 v234, 0x16000, v235
	v_mul_f32_e32 v252, 0xbfb8aa3b, v240
	v_mul_f32_e32 v254, v240, v240
	v_rcp_f32_e32 v254, v254
	v_pk_mul_f32 v[40:41], v[44:45], v[40:41]
	v_pk_mul_f32 v[42:43], v[46:47], v[42:43]
	v_pk_mul_f32 v[32:33], v[36:37], v[32:33]
	v_pk_mul_f32 v[34:35], v[38:39], v[34:35]
	v_pk_mul_f32 v[44:45], v[44:45], v[252:253] op_sel_hi:[1,0]
	v_pk_mul_f32 v[46:47], v[46:47], v[252:253] op_sel_hi:[1,0]
	v_pk_mul_f32 v[36:37], v[36:37], v[252:253] op_sel_hi:[1,0]
	v_pk_mul_f32 v[38:39], v[38:39], v[252:253] op_sel_hi:[1,0]
	v_exp_f32_e32 v44, v44
	v_exp_f32_e32 v45, v45
	v_exp_f32_e32 v46, v46
	v_exp_f32_e32 v47, v47
	v_exp_f32_e32 v36, v36
	v_exp_f32_e32 v37, v37
	v_exp_f32_e32 v38, v38
	v_exp_f32_e32 v39, v39
	v_pk_fma_f32 v[44:45], v[44:45], v[254:255], v[254:255] op_sel_hi:[1,0,0]
	v_pk_fma_f32 v[46:47], v[46:47], v[254:255], v[254:255] op_sel_hi:[1,0,0]
	v_pk_fma_f32 v[36:37], v[36:37], v[254:255], v[254:255] op_sel_hi:[1,0,0]
	v_pk_fma_f32 v[38:39], v[38:39], v[254:255], v[254:255] op_sel_hi:[1,0,0]
	v_rcp_f32_e32 v44, v44
	v_rcp_f32_e32 v45, v45
	v_rcp_f32_e32 v46, v46
	v_rcp_f32_e32 v47, v47
	v_rcp_f32_e32 v36, v36
	v_rcp_f32_e32 v37, v37
	v_rcp_f32_e32 v38, v38
	v_rcp_f32_e32 v39, v39
	v_pk_mul_f32 v[40:41], v[40:41], v[44:45]
	v_pk_mul_f32 v[42:43], v[42:43], v[46:47]
	v_pk_mul_f32 v[32:33], v[32:33], v[36:37]
	v_pk_mul_f32 v[34:35], v[34:35], v[38:39]
	v_cvt_pk_bf16_f32 v40, v40, v41
	v_cvt_pk_bf16_f32 v41, v42, v43
	v_cvt_pk_bf16_f32 v42, v32, v33
	v_cvt_pk_bf16_f32 v43, v34, v35
	global_store_dwordx4 v234, v[40:43], s[10:11]
	v_add_u32_e32 v235, 0x16000, v234
	v_mul_f32_e32 v252, 0xbfb8aa3b, v244
	v_mul_f32_e32 v254, v244, v244
	v_rcp_f32_e32 v254, v254
	v_pk_mul_f32 v[24:25], v[28:29], v[24:25]
	v_pk_mul_f32 v[26:27], v[30:31], v[26:27]
	v_pk_mul_f32 v[16:17], v[20:21], v[16:17]
	v_pk_mul_f32 v[18:19], v[22:23], v[18:19]
	v_pk_mul_f32 v[28:29], v[28:29], v[252:253] op_sel_hi:[1,0]
	v_pk_mul_f32 v[30:31], v[30:31], v[252:253] op_sel_hi:[1,0]
	v_pk_mul_f32 v[20:21], v[20:21], v[252:253] op_sel_hi:[1,0]
	v_pk_mul_f32 v[22:23], v[22:23], v[252:253] op_sel_hi:[1,0]
	v_exp_f32_e32 v28, v28
	v_exp_f32_e32 v29, v29
	v_exp_f32_e32 v30, v30
	v_exp_f32_e32 v31, v31
	v_exp_f32_e32 v20, v20
	v_exp_f32_e32 v21, v21
	v_exp_f32_e32 v22, v22
	v_exp_f32_e32 v23, v23
	v_pk_fma_f32 v[28:29], v[28:29], v[254:255], v[254:255] op_sel_hi:[1,0,0]
	v_pk_fma_f32 v[30:31], v[30:31], v[254:255], v[254:255] op_sel_hi:[1,0,0]
	v_pk_fma_f32 v[20:21], v[20:21], v[254:255], v[254:255] op_sel_hi:[1,0,0]
	v_pk_fma_f32 v[22:23], v[22:23], v[254:255], v[254:255] op_sel_hi:[1,0,0]
	v_rcp_f32_e32 v28, v28
	v_rcp_f32_e32 v29, v29
	v_rcp_f32_e32 v30, v30
	v_rcp_f32_e32 v31, v31
	v_rcp_f32_e32 v20, v20
	v_rcp_f32_e32 v21, v21
	v_rcp_f32_e32 v22, v22
	v_rcp_f32_e32 v23, v23
	v_pk_mul_f32 v[24:25], v[24:25], v[28:29]
	v_pk_mul_f32 v[26:27], v[26:27], v[30:31]
	v_pk_mul_f32 v[16:17], v[16:17], v[20:21]
	v_pk_mul_f32 v[18:19], v[18:19], v[22:23]
	v_cvt_pk_bf16_f32 v24, v24, v25
	v_cvt_pk_bf16_f32 v25, v26, v27
	v_cvt_pk_bf16_f32 v26, v16, v17
	v_cvt_pk_bf16_f32 v27, v18, v19
	global_store_dwordx4 v235, v[24:27], s[10:11]
	v_add_u32_e32 v234, 0x16000, v235
	v_mul_f32_e32 v252, 0xbfb8aa3b, v248
	v_mul_f32_e32 v254, v248, v248
	v_rcp_f32_e32 v254, v254
	v_pk_mul_f32 v[8:9], v[12:13], v[8:9]
	v_pk_mul_f32 v[10:11], v[14:15], v[10:11]
	v_pk_mul_f32 v[0:1], v[4:5], v[0:1]
	v_pk_mul_f32 v[2:3], v[6:7], v[2:3]
	v_pk_mul_f32 v[12:13], v[12:13], v[252:253] op_sel_hi:[1,0]
	v_pk_mul_f32 v[14:15], v[14:15], v[252:253] op_sel_hi:[1,0]
	v_pk_mul_f32 v[4:5], v[4:5], v[252:253] op_sel_hi:[1,0]
	v_pk_mul_f32 v[6:7], v[6:7], v[252:253] op_sel_hi:[1,0]
	v_exp_f32_e32 v12, v12
	v_exp_f32_e32 v13, v13
	v_exp_f32_e32 v14, v14
	v_exp_f32_e32 v15, v15
	v_exp_f32_e32 v4, v4
	v_exp_f32_e32 v5, v5
	v_exp_f32_e32 v6, v6
	v_exp_f32_e32 v7, v7
	v_pk_fma_f32 v[12:13], v[12:13], v[254:255], v[254:255] op_sel_hi:[1,0,0]
	v_pk_fma_f32 v[14:15], v[14:15], v[254:255], v[254:255] op_sel_hi:[1,0,0]
	v_pk_fma_f32 v[4:5], v[4:5], v[254:255], v[254:255] op_sel_hi:[1,0,0]
	v_pk_fma_f32 v[6:7], v[6:7], v[254:255], v[254:255] op_sel_hi:[1,0,0]
	v_rcp_f32_e32 v12, v12
	v_rcp_f32_e32 v13, v13
	v_rcp_f32_e32 v14, v14
	v_rcp_f32_e32 v15, v15
	v_rcp_f32_e32 v4, v4
	v_rcp_f32_e32 v5, v5
	v_rcp_f32_e32 v6, v6
	v_rcp_f32_e32 v7, v7
	v_pk_mul_f32 v[8:9], v[8:9], v[12:13]
	v_pk_mul_f32 v[10:11], v[10:11], v[14:15]
	v_pk_mul_f32 v[0:1], v[0:1], v[4:5]
	v_pk_mul_f32 v[2:3], v[2:3], v[6:7]
	v_cvt_pk_bf16_f32 v8, v8, v9
	v_cvt_pk_bf16_f32 v9, v10, v11
	v_cvt_pk_bf16_f32 v10, v0, v1
	v_cvt_pk_bf16_f32 v11, v2, v3
	global_store_dwordx4 v234, v[8:11], s[10:11]
	s_andn2_b64 vcc, exec, s[6:7]
	s_mov_b64 s[6:7], -1
	s_cbranch_vccnz .LBB0_1093
	s_andn2_b64 vcc, exec, s[8:9]
	s_cbranch_vccnz .LBB0_1092
	s_barrier
	s_branch .LBB0_1092
